# attention loops: NaN-quieting self-max ops dropped (NSA chain head 3->1, DSA 10->4), NSA row-on bit via v_bfe
# baseline (speedup 1.0000x reference)
; #define LAS __attribute__((address_space(3)))
; #define MFMA32(a, b, c) __builtin_amdgcn_mfma_f32_32x32x16_bf16((a), (b), (c), 0, 0, 0)
; DI float fexp2(float x) { return __builtin_amdgcn_exp2f(x); }
; DI float half_max(float v) { return fmaxf(v, __shfl_xor(v, 32)); }
; DI void flash_qk_bias(const LAS unsigned char* kb, const bf16x8 (&qf)[4], f32x16& p0, f32x16& p1, int r32, int h, const bf16x8& m0, const bf16x8& m1, const bf16x8& ef) {
;     p0 = MFMA32(m0, ef, f16zero()); p1 = MFMA32(m1, ef, f16zero());
;     const int sw = (r32 >> 1) & 7;
; #pragma unroll
;     for (int s = 0; s < 4; ++s) {
;         const int off = r32 * 128 + (((2 * s + h) ^ sw) << 4);
;         const bf16x8 a0 = *(const LAS bf16x8*)(kb + off), a1 = *(const LAS bf16x8*)(kb + off + 4096);
;         p0 = MFMA32(a0, qf[s], p0); p1 = MFMA32(a1, qf[s], p1);
;     }
; }
; DI void flash_pv2(FState& sa, FState& sb, f32x16& a0, f32x16& a1, bool rona, f32x16& b0, f32x16& b1, bool ronb, const LAS unsigned char* va, const LAS unsigned char* vbb, int lane) {
;     float mxa = fmaxf(a0[0], a1[0]), mxb = fmaxf(b0[0], b1[0]);
; #pragma unroll
;     for (int r = 1; r < 16; ++r) { asm("v_max3_f32 %0, %1, %2, %3" : "=v"(mxa) : "v"(mxa), "v"(a0[r]), "v"(a1[r])); asm("v_max3_f32 %0, %1, %2, %3" : "=v"(mxb) : "v"(mxb), "v"(b0[r]), "v"(b1[r])); }
;     mxa = half_max(mxa); mxb = half_max(mxb);
;     mxa = rona ? mxa : NINF; mxb = ronb ? mxb : NINF;
;     const bool upa = mxa > sa.m + THR_RAW, upb = mxb > sb.m + THR_RAW;
;     if (__any(upa || upb)) {
;         const float mna = upa ? mxa : sa.m, mnb = upb ? mxb : sb.m;
;         const float ala = upa ? fexp2((sa.m - mna) * SM_C) : 1.0f, alb = upb ? fexp2((sb.m - mnb) * SM_C) : 1.0f;
;         sa.m = mna; sa.l *= ala; sb.m = mnb; sb.l *= alb;
; #pragma unroll
;         for (int r = 0; r < 16; ++r) { sa.o0[r] *= ala; sa.o1[r] *= ala; sb.o0[r] *= alb; sb.o1[r] *= alb; }
;     }
.Ldsa_nomask:
	v_mov_b32_e32 v94, v90
	v_mov_b32_e32 v95, v90
	v_mov_b32_e32 v91, v90
	s_add_i32 s4, s16, 0xffff8000
	v_mov_b32_e32 v86, v90
	v_mov_b32_e32 v87, v90
	s_and_b32 s4, s4, 0x8000
	s_add_i32 s73, s4, 0
	v_mfma_f32_32x32x16_bf16 v[100:115], v[92:95], v[84:87], 0
	v_add_u32_e32 v99, s73, v201
	v_add_u32_e32 v179, v99, v165
	v_add_u32_e32 v187, v99, v216
	v_add_u32_e32 v192, v99, v217
	v_add_u32_e32 v193, v99, v218
	v_mov_b32_e32 v118, v98
	v_mov_b32_e32 v119, v98
	v_mfma_f32_32x32x16_bf16 v[68:83], v[88:91], v[84:87], 0
	ds_read_b128 v[88:91], v179
	ds_read_b128 v[92:95], v179 offset:4096
	v_mov_b32_e32 v99, v98
	s_cmp_lt_u32 s51, s71
	s_cselect_b64 s[4:5], -1, 0
	s_waitcnt lgkmcnt(0)
	v_mfma_f32_32x32x16_bf16 v[100:115], v[88:91], v[132:135], v[100:115]
	v_mfma_f32_32x32x16_bf16 v[68:83], v[92:95], v[132:135], v[68:83]
	ds_read_b128 v[88:91], v187
	ds_read_b128 v[92:95], v187 offset:4096
	s_waitcnt lgkmcnt(0)
	v_mfma_f32_32x32x16_bf16 v[100:115], v[88:91], v[136:139], v[100:115]
	v_mfma_f32_32x32x16_bf16 v[68:83], v[92:95], v[136:139], v[68:83]
	ds_read_b128 v[88:91], v192
	ds_read_b128 v[92:95], v192 offset:4096
	s_waitcnt lgkmcnt(0)
	v_mfma_f32_32x32x16_bf16 v[100:115], v[88:91], v[140:143], v[100:115]
	v_mfma_f32_32x32x16_bf16 v[68:83], v[92:95], v[140:143], v[68:83]
	ds_read_b128 v[88:91], v193
	ds_read_b128 v[92:95], v193 offset:4096
	ds_read_b128 v[182:185], v179 offset:16384
	ds_read_b128 v[188:191], v179 offset:20480
	v_mfma_f32_32x32x16_bf16 v[116:131], v[116:119], v[84:87], 0
	s_waitcnt lgkmcnt(0)
	v_mfma_f32_32x32x16_bf16 v[100:115], v[88:91], v[144:147], v[100:115]
	v_mfma_f32_32x32x16_bf16 v[68:83], v[92:95], v[144:147], v[68:83]
	v_mfma_f32_32x32x16_bf16 v[84:99], v[96:99], v[84:87], 0
	s_nop 10
	v_max_f32_e32 v179, v68, v68
	v_mfma_f32_32x32x16_bf16 v[116:131], v[182:185], v[132:135], v[116:131]
	v_mfma_f32_32x32x16_bf16 v[84:99], v[188:191], v[132:135], v[84:99]
	ds_read_b128 v[182:185], v187 offset:16384
	ds_read_b128 v[188:191], v187 offset:20480
	v_max_f32_e32 v179, v100, v179
	v_max3_f32 v179, v179, v101, v69
	v_max3_f32 v179, v179, v102, v70
	s_waitcnt lgkmcnt(0)
	v_mfma_f32_32x32x16_bf16 v[116:131], v[182:185], v[136:139], v[116:131]
	v_max3_f32 v179, v179, v103, v71
	v_max3_f32 v179, v179, v104, v72
	v_max3_f32 v179, v179, v105, v73
	v_max3_f32 v179, v179, v106, v74
	v_mfma_f32_32x32x16_bf16 v[84:99], v[188:191], v[136:139], v[84:99]
	ds_read_b128 v[182:185], v192 offset:16384
	ds_read_b128 v[188:191], v192 offset:20480
	v_max3_f32 v179, v179, v107, v75
	v_max3_f32 v179, v179, v108, v76
	v_max3_f32 v179, v179, v109, v77
	s_waitcnt lgkmcnt(0)
	v_mfma_f32_32x32x16_bf16 v[116:131], v[182:185], v[140:143], v[116:131]
	ds_read_b128 v[182:185], v193 offset:20480
	v_max3_f32 v179, v179, v110, v78
	v_max3_f32 v179, v179, v111, v79
	v_max3_f32 v179, v179, v112, v80
	v_mfma_f32_32x32x16_bf16 v[84:99], v[188:191], v[140:143], v[84:99]
	v_max3_f32 v179, v179, v113, v81
	v_max3_f32 v179, v179, v114, v82
	s_waitcnt lgkmcnt(0)
	v_mfma_f32_32x32x16_bf16 v[84:99], v[182:185], v[144:147], v[84:99]
	ds_read_b128 v[182:185], v193 offset:16384
	s_waitcnt lgkmcnt(0)
	v_mfma_f32_32x32x16_bf16 v[116:131], v[182:185], v[144:147], v[116:131]
	s_nop 8
	v_max_f32_e32 v187, v84, v84
	v_and_b32_e32 v184, 64, v198
	v_max3_f32 v183, v179, v115, v83
	v_xor_b32_e32 v179, 32, v198
	v_add_u32_e32 v184, 64, v184
	v_cmp_lt_i32_e32 vcc, v179, v184
	v_max_f32_e32 v182, v116, v187
	v_max3_f32 v182, v182, v117, v85
	v_cndmask_b32_e32 v179, v198, v179, vcc
	v_max3_f32 v182, v182, v118, v86
	v_lshlrev_b32_e32 v179, 2, v179
	v_max3_f32 v182, v182, v119, v87
	ds_bpermute_b32 v184, v179, v183
	v_max3_f32 v182, v182, v120, v88
	v_max3_f32 v182, v182, v121, v89
	v_max3_f32 v182, v182, v122, v90
	v_max3_f32 v182, v182, v123, v91
	v_max3_f32 v182, v182, v124, v92
	v_max3_f32 v182, v182, v125, v93
	v_max3_f32 v182, v182, v126, v94
	v_max3_f32 v182, v182, v127, v95
	v_max3_f32 v182, v182, v128, v96
	v_max3_f32 v182, v182, v129, v97
	v_max3_f32 v182, v182, v130, v98
	v_max3_f32 v185, v182, v131, v99
	ds_bpermute_b32 v187, v179, v185
	s_waitcnt lgkmcnt(0)
	v_max_f32_e32 v182, v183, v184
	v_max_f32_e32 v183, v185, v187
	v_cndmask_b32_e64 v183, v186, v183, s[4:5]
	v_pk_add_f32 v[184:185], v[180:181], s[46:47] op_sel_hi:[1,0]
	s_nop 0
	v_cmp_gt_f32_e64 s[6:7], v182, v184
	v_cmp_gt_f32_e64 s[8:9], v183, v185
	s_or_b64 vcc, s[6:7], s[8:9]
	s_cbranch_vccz .LBB0_728
	v_cndmask_b32_e64 v183, v181, v183, s[8:9]
	v_cndmask_b32_e64 v182, v180, v182, s[6:7]
	v_pk_add_f32 v[180:181], v[180:181], v[182:183] neg_lo:[0,1] neg_hi:[0,1]
	s_nop 0
	v_mul_f32_e32 v180, 0x3e38aa3b, v180
	v_mul_f32_e32 v181, 0x3e38aa3b, v181
	v_exp_f32_e32 v181, v181
	v_exp_f32_e32 v180, v180
	v_cndmask_b32_e64 v181, 1.0, v181, s[8:9]
	v_cndmask_b32_e64 v180, 1.0, v180, s[6:7]
	v_pk_mul_f32 v[172:173], v[172:173], v[180:181]
	v_pk_mul_f32 v[66:67], v[66:67], v[180:181] op_sel_hi:[1,0]
	v_pk_mul_f32 v[64:65], v[64:65], v[180:181] op_sel_hi:[1,0]
	v_pk_mul_f32 v[62:63], v[62:63], v[180:181] op_sel_hi:[1,0]
	v_pk_mul_f32 v[60:61], v[60:61], v[180:181] op_sel_hi:[1,0]
	v_pk_mul_f32 v[58:59], v[58:59], v[180:181] op_sel_hi:[1,0]
	v_pk_mul_f32 v[56:57], v[56:57], v[180:181] op_sel_hi:[1,0]
	v_pk_mul_f32 v[54:55], v[54:55], v[180:181] op_sel_hi:[1,0]
	v_pk_mul_f32 v[52:53], v[52:53], v[180:181] op_sel_hi:[1,0]
	v_pk_mul_f32 v[18:19], v[18:19], v[180:181] op_sel_hi:[1,0]
	v_pk_mul_f32 v[16:17], v[16:17], v[180:181] op_sel_hi:[1,0]
	v_pk_mul_f32 v[14:15], v[14:15], v[180:181] op_sel_hi:[1,0]
	v_pk_mul_f32 v[12:13], v[12:13], v[180:181] op_sel_hi:[1,0]
	v_pk_mul_f32 v[10:11], v[10:11], v[180:181] op_sel_hi:[1,0]
	v_pk_mul_f32 v[8:9], v[8:9], v[180:181] op_sel_hi:[1,0]
	v_pk_mul_f32 v[6:7], v[6:7], v[180:181] op_sel_hi:[1,0]
	v_pk_mul_f32 v[4:5], v[4:5], v[180:181] op_sel_hi:[1,0]
	v_mov_b32_e32 v180, v181
	v_pk_mul_f32 v[50:51], v[50:51], v[180:181] op_sel_hi:[1,0]
	v_pk_mul_f32 v[48:49], v[48:49], v[180:181] op_sel_hi:[1,0]
	v_pk_mul_f32 v[46:47], v[46:47], v[180:181] op_sel_hi:[1,0]
	v_pk_mul_f32 v[44:45], v[44:45], v[180:181] op_sel_hi:[1,0]
	v_pk_mul_f32 v[42:43], v[42:43], v[180:181] op_sel_hi:[1,0]
	v_pk_mul_f32 v[40:41], v[40:41], v[180:181] op_sel_hi:[1,0]
	v_pk_mul_f32 v[38:39], v[38:39], v[180:181] op_sel_hi:[1,0]
	v_pk_mul_f32 v[36:37], v[36:37], v[180:181] op_sel_hi:[1,0]
	v_pk_mul_f32 v[34:35], v[34:35], v[180:181] op_sel_hi:[1,0]
	v_pk_mul_f32 v[32:33], v[32:33], v[180:181] op_sel_hi:[1,0]
	v_pk_mul_f32 v[30:31], v[30:31], v[180:181] op_sel_hi:[1,0]
	v_pk_mul_f32 v[28:29], v[28:29], v[180:181] op_sel_hi:[1,0]
	v_pk_mul_f32 v[26:27], v[26:27], v[180:181] op_sel_hi:[1,0]
	v_pk_mul_f32 v[24:25], v[24:25], v[180:181] op_sel_hi:[1,0]
	v_pk_mul_f32 v[22:23], v[22:23], v[180:181] op_sel_hi:[1,0]
	v_pk_mul_f32 v[20:21], v[20:21], v[180:181] op_sel_hi:[1,0]
	v_mov_b64_e32 v[180:181], v[182:183]

.LBB0_745:
	s_add_i32 s10, s52, 5
	s_cmp_gt_u32 s74, s69
	s_cselect_b64 s[8:9], -1, 0
	s_and_b64 vcc, s[8:9], exec
	s_cselect_b32 s8, s10, s74
	v_lshl_or_b32 v2, s8, 6, v194
	s_mov_b64 s[10:11], -1
	s_cbranch_vccnz .LBB0_749
	v_bfe_u32 v4, v196, s74, 1
	v_cmp_eq_u32_e64 s[8:9], 1, v4
	s_cmp_lg_u32 s69, s74
	s_cbranch_scc1 .LBB0_748
	v_cmp_le_i32_e32 vcc, v2, v190
	v_or_b32_e32 v4, 32, v2
	s_nop 0
	v_cndmask_b32_e32 v98, v186, v98, vcc
	v_cmp_le_i32_e32 vcc, v4, v190
	v_or_b32_e32 v4, 33, v2
	s_nop 0
	v_cndmask_b32_e32 v82, v186, v82, vcc
	v_cmp_lt_i32_e32 vcc, v2, v190
	s_nop 1
	v_cndmask_b32_e32 v99, v186, v99, vcc
	v_cmp_le_i32_e32 vcc, v4, v190
	v_or_b32_e32 v4, 2, v2
	s_nop 0
	v_cndmask_b32_e32 v83, v186, v83, vcc
	v_cmp_le_i32_e32 vcc, v4, v190
	v_or_b32_e32 v4, 34, v2
	s_nop 0
	v_cndmask_b32_e32 v100, v186, v100, vcc
	v_cmp_le_i32_e32 vcc, v4, v190
	v_or_b32_e32 v4, 3, v2
	s_nop 0
	v_cndmask_b32_e32 v84, v186, v84, vcc
	v_cmp_le_i32_e32 vcc, v4, v190
	v_or_b32_e32 v4, 35, v2
	s_nop 0
	v_cndmask_b32_e32 v101, v186, v101, vcc
	v_cmp_le_i32_e32 vcc, v4, v190
	v_or_b32_e32 v4, 8, v2
	s_nop 0
	v_cndmask_b32_e32 v85, v186, v85, vcc
	v_cmp_le_i32_e32 vcc, v4, v190
	v_or_b32_e32 v4, 40, v2
	s_nop 0
	v_cndmask_b32_e32 v102, v186, v102, vcc
	v_cmp_le_i32_e32 vcc, v4, v190
	v_or_b32_e32 v4, 9, v2
	s_nop 0
	v_cndmask_b32_e32 v86, v186, v86, vcc
	v_cmp_le_i32_e32 vcc, v4, v190
	v_or_b32_e32 v4, 41, v2
	s_nop 0
	v_cndmask_b32_e32 v103, v186, v103, vcc
	v_cmp_le_i32_e32 vcc, v4, v190
	v_or_b32_e32 v4, 10, v2
	s_nop 0
	v_cndmask_b32_e32 v87, v186, v87, vcc
	v_cmp_le_i32_e32 vcc, v4, v190
	v_or_b32_e32 v4, 42, v2
	s_nop 0
	v_cndmask_b32_e32 v104, v186, v104, vcc
	v_cmp_le_i32_e32 vcc, v4, v190
	v_or_b32_e32 v4, 11, v2
	s_nop 0
	v_cndmask_b32_e32 v88, v186, v88, vcc
	v_cmp_le_i32_e32 vcc, v4, v190
	v_or_b32_e32 v4, 43, v2
	s_nop 0
	v_cndmask_b32_e32 v105, v186, v105, vcc
	v_cmp_le_i32_e32 vcc, v4, v190
	v_or_b32_e32 v4, 16, v2
	s_nop 0
	v_cndmask_b32_e32 v89, v186, v89, vcc
	v_cmp_le_i32_e32 vcc, v4, v190
	v_or_b32_e32 v4, 48, v2
	s_nop 0
	v_cndmask_b32_e32 v106, v186, v106, vcc
	v_cmp_le_i32_e32 vcc, v4, v190
	v_or_b32_e32 v4, 17, v2
	s_nop 0
	v_cndmask_b32_e32 v90, v186, v90, vcc
	v_cmp_le_i32_e32 vcc, v4, v190
	v_or_b32_e32 v4, 49, v2
	s_nop 0
	v_cndmask_b32_e32 v107, v186, v107, vcc
	v_cmp_le_i32_e32 vcc, v4, v190
	v_or_b32_e32 v4, 18, v2
	s_nop 0
	v_cndmask_b32_e32 v91, v186, v91, vcc
	v_cmp_le_i32_e32 vcc, v4, v190
	v_or_b32_e32 v4, 50, v2
	s_nop 0
	v_cndmask_b32_e32 v108, v186, v108, vcc
	v_cmp_le_i32_e32 vcc, v4, v190
	v_or_b32_e32 v4, 19, v2
	s_nop 0
	v_cndmask_b32_e32 v92, v186, v92, vcc
	v_cmp_le_i32_e32 vcc, v4, v190
	v_or_b32_e32 v4, 51, v2
	s_nop 0
	v_cndmask_b32_e32 v109, v186, v109, vcc
	v_cmp_le_i32_e32 vcc, v4, v190
	v_or_b32_e32 v4, 24, v2
	s_nop 0
	v_cndmask_b32_e32 v93, v186, v93, vcc
	v_cmp_le_i32_e32 vcc, v4, v190
	v_or_b32_e32 v4, 56, v2
	s_nop 0
	v_cndmask_b32_e32 v110, v186, v110, vcc
	v_cmp_le_i32_e32 vcc, v4, v190
	v_or_b32_e32 v4, 25, v2
	s_nop 0
	v_cndmask_b32_e32 v94, v186, v94, vcc
	v_cmp_le_i32_e32 vcc, v4, v190
	v_or_b32_e32 v4, 57, v2
	s_nop 0
	v_cndmask_b32_e32 v111, v186, v111, vcc
	v_cmp_le_i32_e32 vcc, v4, v190
	v_or_b32_e32 v4, 26, v2
	s_nop 0
	v_cndmask_b32_e32 v95, v186, v95, vcc
	v_cmp_le_i32_e32 vcc, v4, v190
	v_or_b32_e32 v4, 58, v2
	s_nop 0
	v_cndmask_b32_e32 v112, v186, v112, vcc
	v_cmp_le_i32_e32 vcc, v4, v190
	v_or_b32_e32 v4, 27, v2
	s_nop 0
	v_cndmask_b32_e32 v96, v186, v96, vcc
	v_cmp_le_i32_e32 vcc, v4, v190
	v_or_b32_e32 v4, 59, v2
	s_nop 0
	v_cndmask_b32_e32 v113, v186, v113, vcc
	v_cmp_le_i32_e32 vcc, v4, v190
	s_nop 1
	v_cndmask_b32_e32 v97, v186, v97, vcc

; #define LAS __attribute__((address_space(3)))
; DI float fexp2(float x) { return __builtin_amdgcn_exp2f(x); }
; DI float half_max(float v) { return fmaxf(v, __shfl_xor(v, 32)); }
; DI void flash_pv(FState& st, f32x16& p0, f32x16& p1, bool rowon, const LAS unsigned char* vb, int lane) {
;     float mx = fmaxf(p0[0], p1[0]);
; #pragma unroll
;     for (int r = 1; r < 16; ++r) asm("v_max3_f32 %0, %1, %2, %3" : "=v"(mx) : "v"(mx), "v"(p0[r]), "v"(p1[r]));
;     mx = half_max(mx);
;     mx = rowon ? mx : NINF;
;     const bool upd = mx > st.m + THR_RAW;
;     if (__any(upd)) {
;         const float mn = upd ? mx : st.m;
;         const float alpha = upd ? fexp2((st.m - mn) * SM_C) : 1.0f;
;         st.m = mn; st.l *= alpha;
; #pragma unroll
;         for (int r = 0; r < 16; ++r) { st.o0[r] *= alpha; st.o1[r] *= alpha; }
;     }
.LBB0_753:
	v_max_f32_e32 v2, v98, v82
	s_waitcnt lgkmcnt(3)
	v_mfma_f32_32x32x16_bf16 v[130:145], v[226:229], v[146:149], 0
	v_max3_f32 v2, v2, v99, v83
	v_max3_f32 v2, v2, v100, v84
	s_waitcnt lgkmcnt(2)
	v_mfma_f32_32x32x16_bf16 v[114:129], v[230:233], v[146:149], 0
	ds_read_b128 v[226:229], v223 offset:16384
	ds_read_b128 v[230:233], v223 offset:20480
	v_max3_f32 v2, v2, v101, v85
	v_max3_f32 v2, v2, v102, v86
	s_waitcnt lgkmcnt(3)
	v_mfma_f32_32x32x16_bf16 v[130:145], v[234:237], v[150:153], v[130:145]
	v_max3_f32 v2, v2, v103, v87
	v_max3_f32 v2, v2, v104, v88
	v_max3_f32 v2, v2, v105, v89
	s_waitcnt lgkmcnt(2)
	v_mfma_f32_32x32x16_bf16 v[114:129], v[238:241], v[150:153], v[114:129]
	ds_read_b128 v[234:237], v224 offset:16384
	ds_read_b128 v[238:241], v224 offset:20480
	v_max3_f32 v2, v2, v106, v90
	v_max3_f32 v2, v2, v107, v91
	v_max3_f32 v2, v2, v108, v92
	v_max3_f32 v2, v2, v109, v93
	v_max3_f32 v2, v2, v110, v94
	v_max3_f32 v2, v2, v111, v95
	v_max3_f32 v2, v2, v112, v96
	v_max3_f32 v2, v2, v113, v97
	v_mov_b32_e32 v4, v2
	s_nop 1
	v_permlane32_swap_b32_e32 v4, v2
	s_nop 0
	v_max_f32_e32 v2, v2, v4
	v_cndmask_b32_e64 v2, v186, v2, s[8:9]
	v_add_f32_e32 v4, 0x42317218, v216
	v_cmp_gt_f32_e32 vcc, v2, v4
	s_cbranch_vccz .LBB0_755
	s_nop 0
	v_cndmask_b32_e32 v4, v216, v2, vcc
	v_sub_f32_e32 v2, v216, v4
	v_mul_f32_e32 v2, 0x3e38aa3b, v2
	v_exp_f32_e32 v2, v2
	v_mov_b32_e32 v216, v4
	v_cndmask_b32_e32 v2, 1.0, v2, vcc
	v_mul_f32_e32 v214, v214, v2
	v_pk_mul_f32 v[80:81], v[80:81], v[2:3] op_sel_hi:[1,0]
	v_pk_mul_f32 v[78:79], v[78:79], v[2:3] op_sel_hi:[1,0]
	v_pk_mul_f32 v[76:77], v[76:77], v[2:3] op_sel_hi:[1,0]
	v_pk_mul_f32 v[74:75], v[74:75], v[2:3] op_sel_hi:[1,0]
	v_pk_mul_f32 v[72:73], v[72:73], v[2:3] op_sel_hi:[1,0]
	v_pk_mul_f32 v[70:71], v[70:71], v[2:3] op_sel_hi:[1,0]
	v_pk_mul_f32 v[68:69], v[68:69], v[2:3] op_sel_hi:[1,0]
	v_pk_mul_f32 v[66:67], v[66:67], v[2:3] op_sel_hi:[1,0]
	v_pk_mul_f32 v[64:65], v[64:65], v[2:3] op_sel_hi:[1,0]
	v_pk_mul_f32 v[62:63], v[62:63], v[2:3] op_sel_hi:[1,0]
	v_pk_mul_f32 v[60:61], v[60:61], v[2:3] op_sel_hi:[1,0]
	v_pk_mul_f32 v[58:59], v[58:59], v[2:3] op_sel_hi:[1,0]
	v_pk_mul_f32 v[56:57], v[56:57], v[2:3] op_sel_hi:[1,0]
	v_pk_mul_f32 v[54:55], v[54:55], v[2:3] op_sel_hi:[1,0]
	v_pk_mul_f32 v[52:53], v[52:53], v[2:3] op_sel_hi:[1,0]
	v_pk_mul_f32 v[50:51], v[50:51], v[2:3] op_sel_hi:[1,0]

.LBB0_768:
	s_andn2_b64 vcc, exec, s[10:11]
	s_cbranch_vccnz .LBB0_772
	v_bfe_u32 v4, v196, s77, 1
	s_cmp_lg_u32 s72, s74
	v_cmp_eq_u32_e64 s[8:9], 1, v4
	s_cbranch_scc1 .LBB0_771
	v_cmp_le_i32_e32 vcc, v2, v190
	v_or_b32_e32 v4, 32, v2
	s_nop 0
	v_cndmask_b32_e32 v130, v186, v130, vcc
	v_cmp_le_i32_e32 vcc, v4, v190
	v_or_b32_e32 v4, 33, v2
	s_nop 0
	v_cndmask_b32_e32 v114, v186, v114, vcc
	v_cmp_lt_i32_e32 vcc, v2, v190
	s_nop 1
	v_cndmask_b32_e32 v131, v186, v131, vcc
	v_cmp_le_i32_e32 vcc, v4, v190
	v_or_b32_e32 v4, 2, v2
	s_nop 0
	v_cndmask_b32_e32 v115, v186, v115, vcc
	v_cmp_le_i32_e32 vcc, v4, v190
	v_or_b32_e32 v4, 34, v2
	s_nop 0
	v_cndmask_b32_e32 v132, v186, v132, vcc
	v_cmp_le_i32_e32 vcc, v4, v190
	v_or_b32_e32 v4, 3, v2
	s_nop 0
	v_cndmask_b32_e32 v116, v186, v116, vcc
	v_cmp_le_i32_e32 vcc, v4, v190
	v_or_b32_e32 v4, 35, v2
	s_nop 0
	v_cndmask_b32_e32 v133, v186, v133, vcc
	v_cmp_le_i32_e32 vcc, v4, v190
	v_or_b32_e32 v4, 8, v2
	s_nop 0
	v_cndmask_b32_e32 v117, v186, v117, vcc
	v_cmp_le_i32_e32 vcc, v4, v190
	v_or_b32_e32 v4, 40, v2
	s_nop 0
	v_cndmask_b32_e32 v134, v186, v134, vcc
	v_cmp_le_i32_e32 vcc, v4, v190
	v_or_b32_e32 v4, 9, v2
	s_nop 0
	v_cndmask_b32_e32 v118, v186, v118, vcc
	v_cmp_le_i32_e32 vcc, v4, v190
	v_or_b32_e32 v4, 41, v2
	s_nop 0
	v_cndmask_b32_e32 v135, v186, v135, vcc
	v_cmp_le_i32_e32 vcc, v4, v190
	v_or_b32_e32 v4, 10, v2
	s_nop 0
	v_cndmask_b32_e32 v119, v186, v119, vcc
	v_cmp_le_i32_e32 vcc, v4, v190
	v_or_b32_e32 v4, 42, v2
	s_nop 0
	v_cndmask_b32_e32 v136, v186, v136, vcc
	v_cmp_le_i32_e32 vcc, v4, v190
	v_or_b32_e32 v4, 11, v2
	s_nop 0
	v_cndmask_b32_e32 v120, v186, v120, vcc
	v_cmp_le_i32_e32 vcc, v4, v190
	v_or_b32_e32 v4, 43, v2
	s_nop 0
	v_cndmask_b32_e32 v137, v186, v137, vcc
	v_cmp_le_i32_e32 vcc, v4, v190
	v_or_b32_e32 v4, 16, v2
	s_nop 0
	v_cndmask_b32_e32 v121, v186, v121, vcc
	v_cmp_le_i32_e32 vcc, v4, v190
	v_or_b32_e32 v4, 48, v2
	s_nop 0
	v_cndmask_b32_e32 v138, v186, v138, vcc
	v_cmp_le_i32_e32 vcc, v4, v190
	v_or_b32_e32 v4, 17, v2
	s_nop 0
	v_cndmask_b32_e32 v122, v186, v122, vcc
	v_cmp_le_i32_e32 vcc, v4, v190
	v_or_b32_e32 v4, 49, v2
	s_nop 0
	v_cndmask_b32_e32 v139, v186, v139, vcc
	v_cmp_le_i32_e32 vcc, v4, v190
	v_or_b32_e32 v4, 18, v2
	s_nop 0
	v_cndmask_b32_e32 v123, v186, v123, vcc
	v_cmp_le_i32_e32 vcc, v4, v190
	v_or_b32_e32 v4, 50, v2
	s_nop 0
	v_cndmask_b32_e32 v140, v186, v140, vcc
	v_cmp_le_i32_e32 vcc, v4, v190
	v_or_b32_e32 v4, 19, v2
	s_nop 0
	v_cndmask_b32_e32 v124, v186, v124, vcc
	v_cmp_le_i32_e32 vcc, v4, v190
	v_or_b32_e32 v4, 51, v2
	s_nop 0
	v_cndmask_b32_e32 v141, v186, v141, vcc
	v_cmp_le_i32_e32 vcc, v4, v190
	v_or_b32_e32 v4, 24, v2
	s_nop 0
	v_cndmask_b32_e32 v125, v186, v125, vcc
	v_cmp_le_i32_e32 vcc, v4, v190
	v_or_b32_e32 v4, 56, v2
	s_nop 0
	v_cndmask_b32_e32 v142, v186, v142, vcc
	v_cmp_le_i32_e32 vcc, v4, v190
	v_or_b32_e32 v4, 25, v2
	s_nop 0
	v_cndmask_b32_e32 v126, v186, v126, vcc
	v_cmp_le_i32_e32 vcc, v4, v190
	v_or_b32_e32 v4, 57, v2
	s_nop 0
	v_cndmask_b32_e32 v143, v186, v143, vcc
	v_cmp_le_i32_e32 vcc, v4, v190
	v_or_b32_e32 v4, 26, v2
	s_nop 0
	v_cndmask_b32_e32 v127, v186, v127, vcc
	v_cmp_le_i32_e32 vcc, v4, v190
	v_or_b32_e32 v4, 58, v2
	s_nop 0
	v_cndmask_b32_e32 v144, v186, v144, vcc
	v_cmp_le_i32_e32 vcc, v4, v190
	v_or_b32_e32 v4, 27, v2
	v_or_b32_e32 v2, 59, v2
	v_cndmask_b32_e32 v128, v186, v128, vcc
	v_cmp_le_i32_e32 vcc, v4, v190
	s_nop 1
	v_cndmask_b32_e32 v145, v186, v145, vcc
	v_cmp_le_i32_e32 vcc, v2, v190
	s_nop 1
	v_cndmask_b32_e32 v129, v186, v129, vcc

; #define LAS __attribute__((address_space(3)))
; DI float fexp2(float x) { return __builtin_amdgcn_exp2f(x); }
; DI float half_max(float v) { return fmaxf(v, __shfl_xor(v, 32)); }
; DI void flash_pv(FState& st, f32x16& p0, f32x16& p1, bool rowon, const LAS unsigned char* vb, int lane) {
;     float mx = fmaxf(p0[0], p1[0]);
; #pragma unroll
;     for (int r = 1; r < 16; ++r) asm("v_max3_f32 %0, %1, %2, %3" : "=v"(mx) : "v"(mx), "v"(p0[r]), "v"(p1[r]));
;     mx = half_max(mx);
;     mx = rowon ? mx : NINF;
;     const bool upd = mx > st.m + THR_RAW;
;     if (__any(upd)) {
;         const float mn = upd ? mx : st.m;
;         const float alpha = upd ? fexp2((st.m - mn) * SM_C) : 1.0f;
;         st.m = mn; st.l *= alpha;
; #pragma unroll
;         for (int r = 0; r < 16; ++r) { st.o0[r] *= alpha; st.o1[r] *= alpha; }
;     }
.LBB0_772:
	v_max_f32_e32 v2, v130, v114
	s_waitcnt lgkmcnt(3)
	v_mfma_f32_32x32x16_bf16 v[98:113], v[226:229], v[146:149], 0
	v_max3_f32 v2, v2, v131, v115
	v_max3_f32 v2, v2, v132, v116
	v_max3_f32 v2, v2, v133, v117
	v_max3_f32 v2, v2, v134, v118
	s_waitcnt lgkmcnt(2)
	v_mfma_f32_32x32x16_bf16 v[82:97], v[230:233], v[146:149], 0
	ds_read_b128 v[226:229], v223 offset:32768
	ds_read_b128 v[230:233], v223 offset:36864
	v_max3_f32 v2, v2, v135, v119
	v_max3_f32 v2, v2, v136, v120
	v_max3_f32 v2, v2, v137, v121
	v_max3_f32 v2, v2, v138, v122
	s_waitcnt lgkmcnt(3)
	v_mfma_f32_32x32x16_bf16 v[98:113], v[234:237], v[150:153], v[98:113]
	v_max3_f32 v2, v2, v139, v123
	v_max3_f32 v2, v2, v140, v124
	v_max3_f32 v2, v2, v141, v125
	v_max3_f32 v2, v2, v142, v126
	s_waitcnt lgkmcnt(2)
	v_mfma_f32_32x32x16_bf16 v[82:97], v[238:241], v[150:153], v[82:97]
	ds_read_b128 v[234:237], v224 offset:32768
	ds_read_b128 v[238:241], v224 offset:36864
	v_max3_f32 v2, v2, v143, v127
	v_max3_f32 v2, v2, v144, v128
	v_max3_f32 v2, v2, v145, v129
	v_mov_b32_e32 v4, v2
	s_nop 1
	v_permlane32_swap_b32_e32 v4, v2
	s_nop 0
	v_max_f32_e32 v2, v2, v4
	v_cndmask_b32_e64 v2, v186, v2, s[8:9]
	v_add_f32_e32 v4, 0x42317218, v216
	v_cmp_gt_f32_e32 vcc, v2, v4
	s_cbranch_vccz .LBB0_774
	s_nop 0
	v_cndmask_b32_e32 v4, v216, v2, vcc
	v_sub_f32_e32 v2, v216, v4
	v_mul_f32_e32 v2, 0x3e38aa3b, v2
	v_exp_f32_e32 v2, v2
	v_mov_b32_e32 v216, v4
	v_cndmask_b32_e32 v2, 1.0, v2, vcc
	v_mul_f32_e32 v214, v214, v2
	v_pk_mul_f32 v[80:81], v[80:81], v[2:3] op_sel_hi:[1,0]
	v_pk_mul_f32 v[78:79], v[78:79], v[2:3] op_sel_hi:[1,0]
	v_pk_mul_f32 v[76:77], v[76:77], v[2:3] op_sel_hi:[1,0]
	v_pk_mul_f32 v[74:75], v[74:75], v[2:3] op_sel_hi:[1,0]
	v_pk_mul_f32 v[72:73], v[72:73], v[2:3] op_sel_hi:[1,0]
	v_pk_mul_f32 v[70:71], v[70:71], v[2:3] op_sel_hi:[1,0]
	v_pk_mul_f32 v[68:69], v[68:69], v[2:3] op_sel_hi:[1,0]
	v_pk_mul_f32 v[66:67], v[66:67], v[2:3] op_sel_hi:[1,0]
	v_pk_mul_f32 v[64:65], v[64:65], v[2:3] op_sel_hi:[1,0]
	v_pk_mul_f32 v[62:63], v[62:63], v[2:3] op_sel_hi:[1,0]
	v_pk_mul_f32 v[60:61], v[60:61], v[2:3] op_sel_hi:[1,0]
	v_pk_mul_f32 v[58:59], v[58:59], v[2:3] op_sel_hi:[1,0]
	v_pk_mul_f32 v[56:57], v[56:57], v[2:3] op_sel_hi:[1,0]
	v_pk_mul_f32 v[54:55], v[54:55], v[2:3] op_sel_hi:[1,0]
	v_pk_mul_f32 v[52:53], v[52:53], v[2:3] op_sel_hi:[1,0]
	v_pk_mul_f32 v[50:51], v[50:51], v[2:3] op_sel_hi:[1,0]

.LBB0_785:
	s_add_i32 s10, s52, 3
	s_cmp_gt_u32 s76, s69
	s_cselect_b64 s[8:9], -1, 0
	s_and_b64 vcc, s[8:9], exec
	s_cselect_b32 s8, s10, s76
	v_lshl_or_b32 v2, s8, 6, v194
	s_mov_b64 s[10:11], -1
	s_cbranch_vccnz .LBB0_789
	v_bfe_u32 v4, v196, s76, 1
	v_cmp_eq_u32_e64 s[8:9], 1, v4
	s_cmp_lg_u32 s71, s74
	s_cbranch_scc1 .LBB0_788
	v_cmp_le_i32_e32 vcc, v2, v190
	v_or_b32_e32 v4, 32, v2
	s_nop 0
	v_cndmask_b32_e32 v98, v186, v98, vcc
	v_cmp_le_i32_e32 vcc, v4, v190
	v_or_b32_e32 v4, 33, v2
	s_nop 0
	v_cndmask_b32_e32 v82, v186, v82, vcc
	v_cmp_lt_i32_e32 vcc, v2, v190
	s_nop 1
	v_cndmask_b32_e32 v99, v186, v99, vcc
	v_cmp_le_i32_e32 vcc, v4, v190
	v_or_b32_e32 v4, 2, v2
	s_nop 0
	v_cndmask_b32_e32 v83, v186, v83, vcc
	v_cmp_le_i32_e32 vcc, v4, v190
	v_or_b32_e32 v4, 34, v2
	s_nop 0
	v_cndmask_b32_e32 v100, v186, v100, vcc
	v_cmp_le_i32_e32 vcc, v4, v190
	v_or_b32_e32 v4, 3, v2
	s_nop 0
	v_cndmask_b32_e32 v84, v186, v84, vcc
	v_cmp_le_i32_e32 vcc, v4, v190
	v_or_b32_e32 v4, 35, v2
	s_nop 0
	v_cndmask_b32_e32 v101, v186, v101, vcc
	v_cmp_le_i32_e32 vcc, v4, v190
	v_or_b32_e32 v4, 8, v2
	s_nop 0
	v_cndmask_b32_e32 v85, v186, v85, vcc
	v_cmp_le_i32_e32 vcc, v4, v190
	v_or_b32_e32 v4, 40, v2
	s_nop 0
	v_cndmask_b32_e32 v102, v186, v102, vcc
	v_cmp_le_i32_e32 vcc, v4, v190
	v_or_b32_e32 v4, 9, v2
	s_nop 0
	v_cndmask_b32_e32 v86, v186, v86, vcc
	v_cmp_le_i32_e32 vcc, v4, v190
	v_or_b32_e32 v4, 41, v2
	s_nop 0
	v_cndmask_b32_e32 v103, v186, v103, vcc
	v_cmp_le_i32_e32 vcc, v4, v190
	v_or_b32_e32 v4, 10, v2
	s_nop 0
	v_cndmask_b32_e32 v87, v186, v87, vcc
	v_cmp_le_i32_e32 vcc, v4, v190
	v_or_b32_e32 v4, 42, v2
	s_nop 0
	v_cndmask_b32_e32 v104, v186, v104, vcc
	v_cmp_le_i32_e32 vcc, v4, v190
	v_or_b32_e32 v4, 11, v2
	s_nop 0
	v_cndmask_b32_e32 v88, v186, v88, vcc
	v_cmp_le_i32_e32 vcc, v4, v190
	v_or_b32_e32 v4, 43, v2
	s_nop 0
	v_cndmask_b32_e32 v105, v186, v105, vcc
	v_cmp_le_i32_e32 vcc, v4, v190
	v_or_b32_e32 v4, 16, v2
	s_nop 0
	v_cndmask_b32_e32 v89, v186, v89, vcc
	v_cmp_le_i32_e32 vcc, v4, v190
	v_or_b32_e32 v4, 48, v2
	s_nop 0
	v_cndmask_b32_e32 v106, v186, v106, vcc
	v_cmp_le_i32_e32 vcc, v4, v190
	v_or_b32_e32 v4, 17, v2
	s_nop 0
	v_cndmask_b32_e32 v90, v186, v90, vcc
	v_cmp_le_i32_e32 vcc, v4, v190
	v_or_b32_e32 v4, 49, v2
	s_nop 0
	v_cndmask_b32_e32 v107, v186, v107, vcc
	v_cmp_le_i32_e32 vcc, v4, v190
	v_or_b32_e32 v4, 18, v2
	s_nop 0
	v_cndmask_b32_e32 v91, v186, v91, vcc
	v_cmp_le_i32_e32 vcc, v4, v190
	v_or_b32_e32 v4, 50, v2
	s_nop 0
	v_cndmask_b32_e32 v108, v186, v108, vcc
	v_cmp_le_i32_e32 vcc, v4, v190
	v_or_b32_e32 v4, 19, v2
	s_nop 0
	v_cndmask_b32_e32 v92, v186, v92, vcc
	v_cmp_le_i32_e32 vcc, v4, v190
	v_or_b32_e32 v4, 51, v2
	s_nop 0
	v_cndmask_b32_e32 v109, v186, v109, vcc
	v_cmp_le_i32_e32 vcc, v4, v190
	v_or_b32_e32 v4, 24, v2
	s_nop 0
	v_cndmask_b32_e32 v93, v186, v93, vcc
	v_cmp_le_i32_e32 vcc, v4, v190
	v_or_b32_e32 v4, 56, v2
	s_nop 0
	v_cndmask_b32_e32 v110, v186, v110, vcc
	v_cmp_le_i32_e32 vcc, v4, v190
	v_or_b32_e32 v4, 25, v2
	s_nop 0
	v_cndmask_b32_e32 v94, v186, v94, vcc
	v_cmp_le_i32_e32 vcc, v4, v190
	v_or_b32_e32 v4, 57, v2
	s_nop 0
	v_cndmask_b32_e32 v111, v186, v111, vcc
	v_cmp_le_i32_e32 vcc, v4, v190
	v_or_b32_e32 v4, 26, v2
	s_nop 0
	v_cndmask_b32_e32 v95, v186, v95, vcc
	v_cmp_le_i32_e32 vcc, v4, v190
	v_or_b32_e32 v4, 58, v2
	s_nop 0
	v_cndmask_b32_e32 v112, v186, v112, vcc
	v_cmp_le_i32_e32 vcc, v4, v190
	v_or_b32_e32 v4, 27, v2
	s_nop 0
	v_cndmask_b32_e32 v96, v186, v96, vcc
	v_cmp_le_i32_e32 vcc, v4, v190
	v_or_b32_e32 v4, 59, v2
	s_nop 0
	v_cndmask_b32_e32 v113, v186, v113, vcc
	v_cmp_le_i32_e32 vcc, v4, v190
	s_nop 1
	v_cndmask_b32_e32 v97, v186, v97, vcc

; #define LAS __attribute__((address_space(3)))
; DI float fexp2(float x) { return __builtin_amdgcn_exp2f(x); }
; DI float half_max(float v) { return fmaxf(v, __shfl_xor(v, 32)); }
; DI void flash_pv(FState& st, f32x16& p0, f32x16& p1, bool rowon, const LAS unsigned char* vb, int lane) {
;     float mx = fmaxf(p0[0], p1[0]);
; #pragma unroll
;     for (int r = 1; r < 16; ++r) asm("v_max3_f32 %0, %1, %2, %3" : "=v"(mx) : "v"(mx), "v"(p0[r]), "v"(p1[r]));
;     mx = half_max(mx);
;     mx = rowon ? mx : NINF;
;     const bool upd = mx > st.m + THR_RAW;
;     if (__any(upd)) {
;         const float mn = upd ? mx : st.m;
;         const float alpha = upd ? fexp2((st.m - mn) * SM_C) : 1.0f;
;         st.m = mn; st.l *= alpha;
; #pragma unroll
;         for (int r = 0; r < 16; ++r) { st.o0[r] *= alpha; st.o1[r] *= alpha; }
;     }
.LBB0_793:
	v_max_f32_e32 v2, v98, v82
	s_waitcnt lgkmcnt(3)
	v_mfma_f32_32x32x16_bf16 v[130:145], v[226:229], v[146:149], 0
	v_max3_f32 v2, v2, v99, v83
	v_max3_f32 v2, v2, v100, v84
	v_max3_f32 v2, v2, v101, v85
	v_max3_f32 v2, v2, v102, v86
	s_waitcnt lgkmcnt(2)
	v_mfma_f32_32x32x16_bf16 v[114:129], v[230:233], v[146:149], 0
	ds_read_b128 v[226:229], v223
	ds_read_b128 v[230:233], v223 offset:4096
	v_max3_f32 v2, v2, v103, v87
	v_max3_f32 v2, v2, v104, v88
	v_max3_f32 v2, v2, v105, v89
	v_max3_f32 v2, v2, v106, v90
	s_waitcnt lgkmcnt(3)
	v_mfma_f32_32x32x16_bf16 v[130:145], v[234:237], v[150:153], v[130:145]
	v_max3_f32 v2, v2, v107, v91
	v_max3_f32 v2, v2, v108, v92
	v_max3_f32 v2, v2, v109, v93
	v_max3_f32 v2, v2, v110, v94
	s_waitcnt lgkmcnt(2)
	v_mfma_f32_32x32x16_bf16 v[114:129], v[238:241], v[150:153], v[114:129]
	ds_read_b128 v[234:237], v224
	ds_read_b128 v[238:241], v224 offset:4096
	v_max3_f32 v2, v2, v111, v95
	v_max3_f32 v2, v2, v112, v96
	v_max3_f32 v2, v2, v113, v97
	v_mov_b32_e32 v4, v2
	s_nop 1
	v_permlane32_swap_b32_e32 v4, v2
	s_nop 0
	v_max_f32_e32 v2, v2, v4
	v_cndmask_b32_e64 v2, v186, v2, s[8:9]
	v_add_f32_e32 v4, 0x42317218, v216
	v_cmp_gt_f32_e32 vcc, v2, v4
	s_cbranch_vccz .LBB0_795
	s_nop 0
	v_cndmask_b32_e32 v4, v216, v2, vcc
	v_sub_f32_e32 v2, v216, v4
	v_mul_f32_e32 v2, 0x3e38aa3b, v2
	v_exp_f32_e32 v2, v2
	v_mov_b32_e32 v216, v4
	v_cndmask_b32_e32 v2, 1.0, v2, vcc
	v_mul_f32_e32 v214, v214, v2
	v_pk_mul_f32 v[80:81], v[80:81], v[2:3] op_sel_hi:[1,0]
	v_pk_mul_f32 v[78:79], v[78:79], v[2:3] op_sel_hi:[1,0]
	v_pk_mul_f32 v[76:77], v[76:77], v[2:3] op_sel_hi:[1,0]
	v_pk_mul_f32 v[74:75], v[74:75], v[2:3] op_sel_hi:[1,0]
	v_pk_mul_f32 v[72:73], v[72:73], v[2:3] op_sel_hi:[1,0]
	v_pk_mul_f32 v[70:71], v[70:71], v[2:3] op_sel_hi:[1,0]
	v_pk_mul_f32 v[68:69], v[68:69], v[2:3] op_sel_hi:[1,0]
	v_pk_mul_f32 v[66:67], v[66:67], v[2:3] op_sel_hi:[1,0]
	v_pk_mul_f32 v[64:65], v[64:65], v[2:3] op_sel_hi:[1,0]
	v_pk_mul_f32 v[62:63], v[62:63], v[2:3] op_sel_hi:[1,0]
	v_pk_mul_f32 v[60:61], v[60:61], v[2:3] op_sel_hi:[1,0]
	v_pk_mul_f32 v[58:59], v[58:59], v[2:3] op_sel_hi:[1,0]
	v_pk_mul_f32 v[56:57], v[56:57], v[2:3] op_sel_hi:[1,0]
	v_pk_mul_f32 v[54:55], v[54:55], v[2:3] op_sel_hi:[1,0]
	v_pk_mul_f32 v[52:53], v[52:53], v[2:3] op_sel_hi:[1,0]
	v_pk_mul_f32 v[50:51], v[50:51], v[2:3] op_sel_hi:[1,0]

.Lnq_745:
	s_add_i32 s10, s52, 5
	s_cmp_gt_u32 s74, s69
	s_cselect_b64 s[8:9], -1, 0
	s_and_b64 vcc, s[8:9], exec
	s_cselect_b32 s8, s10, s74
	v_lshl_or_b32 v2, s8, 6, v194
	s_mov_b64 s[10:11], -1
	s_cbranch_vccnz .Lnq_749
	v_bfe_u32 v4, v196, s74, 1
	v_cmp_eq_u32_e64 s[8:9], 1, v4
	s_cmp_lg_u32 s69, s74
	s_cbranch_scc1 .Lnq_748
	v_cmp_le_i32_e32 vcc, v2, v190
	v_or_b32_e32 v4, 32, v2
	s_nop 0
	v_cndmask_b32_e32 v130, v186, v130, vcc
	v_cmp_le_i32_e32 vcc, v4, v190
	v_or_b32_e32 v4, 33, v2
	s_nop 0
	v_cndmask_b32_e32 v114, v186, v114, vcc
	v_cmp_lt_i32_e32 vcc, v2, v190
	s_nop 1
	v_cndmask_b32_e32 v131, v186, v131, vcc
	v_cmp_le_i32_e32 vcc, v4, v190
	v_or_b32_e32 v4, 2, v2
	s_nop 0
	v_cndmask_b32_e32 v115, v186, v115, vcc
	v_cmp_le_i32_e32 vcc, v4, v190
	v_or_b32_e32 v4, 34, v2
	s_nop 0
	v_cndmask_b32_e32 v132, v186, v132, vcc
	v_cmp_le_i32_e32 vcc, v4, v190
	v_or_b32_e32 v4, 3, v2
	s_nop 0
	v_cndmask_b32_e32 v116, v186, v116, vcc
	v_cmp_le_i32_e32 vcc, v4, v190
	v_or_b32_e32 v4, 35, v2
	s_nop 0
	v_cndmask_b32_e32 v133, v186, v133, vcc
	v_cmp_le_i32_e32 vcc, v4, v190
	v_or_b32_e32 v4, 8, v2
	s_nop 0
	v_cndmask_b32_e32 v117, v186, v117, vcc
	v_cmp_le_i32_e32 vcc, v4, v190
	v_or_b32_e32 v4, 40, v2
	s_nop 0
	v_cndmask_b32_e32 v134, v186, v134, vcc
	v_cmp_le_i32_e32 vcc, v4, v190
	v_or_b32_e32 v4, 9, v2
	s_nop 0
	v_cndmask_b32_e32 v118, v186, v118, vcc
	v_cmp_le_i32_e32 vcc, v4, v190
	v_or_b32_e32 v4, 41, v2
	s_nop 0
	v_cndmask_b32_e32 v135, v186, v135, vcc
	v_cmp_le_i32_e32 vcc, v4, v190
	v_or_b32_e32 v4, 10, v2
	s_nop 0
	v_cndmask_b32_e32 v119, v186, v119, vcc
	v_cmp_le_i32_e32 vcc, v4, v190
	v_or_b32_e32 v4, 42, v2
	s_nop 0
	v_cndmask_b32_e32 v136, v186, v136, vcc
	v_cmp_le_i32_e32 vcc, v4, v190
	v_or_b32_e32 v4, 11, v2
	s_nop 0
	v_cndmask_b32_e32 v120, v186, v120, vcc
	v_cmp_le_i32_e32 vcc, v4, v190
	v_or_b32_e32 v4, 43, v2
	s_nop 0
	v_cndmask_b32_e32 v137, v186, v137, vcc
	v_cmp_le_i32_e32 vcc, v4, v190
	v_or_b32_e32 v4, 16, v2
	s_nop 0
	v_cndmask_b32_e32 v121, v186, v121, vcc
	v_cmp_le_i32_e32 vcc, v4, v190
	v_or_b32_e32 v4, 48, v2
	s_nop 0
	v_cndmask_b32_e32 v138, v186, v138, vcc
	v_cmp_le_i32_e32 vcc, v4, v190
	v_or_b32_e32 v4, 17, v2
	s_nop 0
	v_cndmask_b32_e32 v122, v186, v122, vcc
	v_cmp_le_i32_e32 vcc, v4, v190
	v_or_b32_e32 v4, 49, v2
	s_nop 0
	v_cndmask_b32_e32 v139, v186, v139, vcc
	v_cmp_le_i32_e32 vcc, v4, v190
	v_or_b32_e32 v4, 18, v2
	s_nop 0
	v_cndmask_b32_e32 v123, v186, v123, vcc
	v_cmp_le_i32_e32 vcc, v4, v190
	v_or_b32_e32 v4, 50, v2
	s_nop 0
	v_cndmask_b32_e32 v140, v186, v140, vcc
	v_cmp_le_i32_e32 vcc, v4, v190
	v_or_b32_e32 v4, 19, v2
	s_nop 0
	v_cndmask_b32_e32 v124, v186, v124, vcc
	v_cmp_le_i32_e32 vcc, v4, v190
	v_or_b32_e32 v4, 51, v2
	s_nop 0
	v_cndmask_b32_e32 v141, v186, v141, vcc
	v_cmp_le_i32_e32 vcc, v4, v190
	v_or_b32_e32 v4, 24, v2
	s_nop 0
	v_cndmask_b32_e32 v125, v186, v125, vcc
	v_cmp_le_i32_e32 vcc, v4, v190
	v_or_b32_e32 v4, 56, v2
	s_nop 0
	v_cndmask_b32_e32 v142, v186, v142, vcc
	v_cmp_le_i32_e32 vcc, v4, v190
	v_or_b32_e32 v4, 25, v2
	s_nop 0
	v_cndmask_b32_e32 v126, v186, v126, vcc
	v_cmp_le_i32_e32 vcc, v4, v190
	v_or_b32_e32 v4, 57, v2
	s_nop 0
	v_cndmask_b32_e32 v143, v186, v143, vcc
	v_cmp_le_i32_e32 vcc, v4, v190
	v_or_b32_e32 v4, 26, v2
	s_nop 0
	v_cndmask_b32_e32 v127, v186, v127, vcc
	v_cmp_le_i32_e32 vcc, v4, v190
	v_or_b32_e32 v4, 58, v2
	s_nop 0
	v_cndmask_b32_e32 v144, v186, v144, vcc
	v_cmp_le_i32_e32 vcc, v4, v190
	v_or_b32_e32 v4, 27, v2
	s_nop 0
	v_cndmask_b32_e32 v128, v186, v128, vcc
	v_cmp_le_i32_e32 vcc, v4, v190
	v_or_b32_e32 v4, 59, v2
	s_nop 0
	v_cndmask_b32_e32 v145, v186, v145, vcc
	v_cmp_le_i32_e32 vcc, v4, v190
	s_nop 1
	v_cndmask_b32_e32 v129, v186, v129, vcc

; #define LAS __attribute__((address_space(3)))
; DI float fexp2(float x) { return __builtin_amdgcn_exp2f(x); }
; DI float half_max(float v) { return fmaxf(v, __shfl_xor(v, 32)); }
; DI void flash_pv(FState& st, f32x16& p0, f32x16& p1, bool rowon, const LAS unsigned char* vb, int lane) {
;     float mx = fmaxf(p0[0], p1[0]);
; #pragma unroll
;     for (int r = 1; r < 16; ++r) asm("v_max3_f32 %0, %1, %2, %3" : "=v"(mx) : "v"(mx), "v"(p0[r]), "v"(p1[r]));
;     mx = half_max(mx);
;     mx = rowon ? mx : NINF;
;     const bool upd = mx > st.m + THR_RAW;
;     if (__any(upd)) {
;         const float mn = upd ? mx : st.m;
;         const float alpha = upd ? fexp2((st.m - mn) * SM_C) : 1.0f;
;         st.m = mn; st.l *= alpha;
; #pragma unroll
;         for (int r = 0; r < 16; ++r) { st.o0[r] *= alpha; st.o1[r] *= alpha; }
;     }
.Lnq_753:
	v_max_f32_e32 v2, v130, v114
	s_waitcnt lgkmcnt(3)
	v_mfma_f32_32x32x16_bf16 v[98:113], v[226:229], v[146:149], 0
	v_max3_f32 v2, v2, v131, v115
	v_max3_f32 v2, v2, v132, v116
	s_waitcnt lgkmcnt(2)
	v_mfma_f32_32x32x16_bf16 v[82:97], v[230:233], v[146:149], 0
	ds_read_b128 v[226:229], v223 offset:16384
	ds_read_b128 v[230:233], v223 offset:20480
	v_max3_f32 v2, v2, v133, v117
	v_max3_f32 v2, v2, v134, v118
	s_waitcnt lgkmcnt(3)
	v_mfma_f32_32x32x16_bf16 v[98:113], v[234:237], v[150:153], v[98:113]
	v_max3_f32 v2, v2, v135, v119
	v_max3_f32 v2, v2, v136, v120
	v_max3_f32 v2, v2, v137, v121
	s_waitcnt lgkmcnt(2)
	v_mfma_f32_32x32x16_bf16 v[82:97], v[238:241], v[150:153], v[82:97]
	ds_read_b128 v[234:237], v224 offset:16384
	ds_read_b128 v[238:241], v224 offset:20480
	v_max3_f32 v2, v2, v138, v122
	v_max3_f32 v2, v2, v139, v123
	v_max3_f32 v2, v2, v140, v124
	v_max3_f32 v2, v2, v141, v125
	v_max3_f32 v2, v2, v142, v126
	v_max3_f32 v2, v2, v143, v127
	v_max3_f32 v2, v2, v144, v128
	v_max3_f32 v2, v2, v145, v129
	v_mov_b32_e32 v4, v2
	s_nop 1
	v_permlane32_swap_b32_e32 v4, v2
	s_nop 0
	v_max_f32_e32 v2, v2, v4
	v_cndmask_b32_e64 v2, v186, v2, s[8:9]
	v_add_f32_e32 v4, 0x42317218, v216
	v_cmp_gt_f32_e32 vcc, v2, v4
	s_cbranch_vccz .Lnq_755
	s_nop 0
	v_cndmask_b32_e32 v4, v216, v2, vcc
	v_sub_f32_e32 v2, v216, v4
	v_mul_f32_e32 v2, 0x3e38aa3b, v2
	v_exp_f32_e32 v2, v2
	v_mov_b32_e32 v216, v4
	v_cndmask_b32_e32 v2, 1.0, v2, vcc
	v_mul_f32_e32 v214, v214, v2
	v_pk_mul_f32 v[80:81], v[80:81], v[2:3] op_sel_hi:[1,0]
	v_pk_mul_f32 v[78:79], v[78:79], v[2:3] op_sel_hi:[1,0]
	v_pk_mul_f32 v[76:77], v[76:77], v[2:3] op_sel_hi:[1,0]
	v_pk_mul_f32 v[74:75], v[74:75], v[2:3] op_sel_hi:[1,0]
	v_pk_mul_f32 v[72:73], v[72:73], v[2:3] op_sel_hi:[1,0]
	v_pk_mul_f32 v[70:71], v[70:71], v[2:3] op_sel_hi:[1,0]
	v_pk_mul_f32 v[68:69], v[68:69], v[2:3] op_sel_hi:[1,0]
	v_pk_mul_f32 v[66:67], v[66:67], v[2:3] op_sel_hi:[1,0]
	v_pk_mul_f32 v[64:65], v[64:65], v[2:3] op_sel_hi:[1,0]
	v_pk_mul_f32 v[62:63], v[62:63], v[2:3] op_sel_hi:[1,0]
	v_pk_mul_f32 v[60:61], v[60:61], v[2:3] op_sel_hi:[1,0]
	v_pk_mul_f32 v[58:59], v[58:59], v[2:3] op_sel_hi:[1,0]
	v_pk_mul_f32 v[56:57], v[56:57], v[2:3] op_sel_hi:[1,0]
	v_pk_mul_f32 v[54:55], v[54:55], v[2:3] op_sel_hi:[1,0]
	v_pk_mul_f32 v[52:53], v[52:53], v[2:3] op_sel_hi:[1,0]
	v_pk_mul_f32 v[50:51], v[50:51], v[2:3] op_sel_hi:[1,0]

.Lnq_768:
	s_andn2_b64 vcc, exec, s[10:11]
	s_cbranch_vccnz .Lnq_772
	v_bfe_u32 v4, v196, s77, 1
	s_cmp_lg_u32 s72, s74
	v_cmp_eq_u32_e64 s[8:9], 1, v4
	s_cbranch_scc1 .Lnq_771
	v_cmp_le_i32_e32 vcc, v2, v190
	v_or_b32_e32 v4, 32, v2
	s_nop 0
	v_cndmask_b32_e32 v98, v186, v98, vcc
	v_cmp_le_i32_e32 vcc, v4, v190
	v_or_b32_e32 v4, 33, v2
	s_nop 0
	v_cndmask_b32_e32 v82, v186, v82, vcc
	v_cmp_lt_i32_e32 vcc, v2, v190
	s_nop 1
	v_cndmask_b32_e32 v99, v186, v99, vcc
	v_cmp_le_i32_e32 vcc, v4, v190
	v_or_b32_e32 v4, 2, v2
	s_nop 0
	v_cndmask_b32_e32 v83, v186, v83, vcc
	v_cmp_le_i32_e32 vcc, v4, v190
	v_or_b32_e32 v4, 34, v2
	s_nop 0
	v_cndmask_b32_e32 v100, v186, v100, vcc
	v_cmp_le_i32_e32 vcc, v4, v190
	v_or_b32_e32 v4, 3, v2
	s_nop 0
	v_cndmask_b32_e32 v84, v186, v84, vcc
	v_cmp_le_i32_e32 vcc, v4, v190
	v_or_b32_e32 v4, 35, v2
	s_nop 0
	v_cndmask_b32_e32 v101, v186, v101, vcc
	v_cmp_le_i32_e32 vcc, v4, v190
	v_or_b32_e32 v4, 8, v2
	s_nop 0
	v_cndmask_b32_e32 v85, v186, v85, vcc
	v_cmp_le_i32_e32 vcc, v4, v190
	v_or_b32_e32 v4, 40, v2
	s_nop 0
	v_cndmask_b32_e32 v102, v186, v102, vcc
	v_cmp_le_i32_e32 vcc, v4, v190
	v_or_b32_e32 v4, 9, v2
	s_nop 0
	v_cndmask_b32_e32 v86, v186, v86, vcc
	v_cmp_le_i32_e32 vcc, v4, v190
	v_or_b32_e32 v4, 41, v2
	s_nop 0
	v_cndmask_b32_e32 v103, v186, v103, vcc
	v_cmp_le_i32_e32 vcc, v4, v190
	v_or_b32_e32 v4, 10, v2
	s_nop 0
	v_cndmask_b32_e32 v87, v186, v87, vcc
	v_cmp_le_i32_e32 vcc, v4, v190
	v_or_b32_e32 v4, 42, v2
	s_nop 0
	v_cndmask_b32_e32 v104, v186, v104, vcc
	v_cmp_le_i32_e32 vcc, v4, v190
	v_or_b32_e32 v4, 11, v2
	s_nop 0
	v_cndmask_b32_e32 v88, v186, v88, vcc
	v_cmp_le_i32_e32 vcc, v4, v190
	v_or_b32_e32 v4, 43, v2
	s_nop 0
	v_cndmask_b32_e32 v105, v186, v105, vcc
	v_cmp_le_i32_e32 vcc, v4, v190
	v_or_b32_e32 v4, 16, v2
	s_nop 0
	v_cndmask_b32_e32 v89, v186, v89, vcc
	v_cmp_le_i32_e32 vcc, v4, v190
	v_or_b32_e32 v4, 48, v2
	s_nop 0
	v_cndmask_b32_e32 v106, v186, v106, vcc
	v_cmp_le_i32_e32 vcc, v4, v190
	v_or_b32_e32 v4, 17, v2
	s_nop 0
	v_cndmask_b32_e32 v90, v186, v90, vcc
	v_cmp_le_i32_e32 vcc, v4, v190
	v_or_b32_e32 v4, 49, v2
	s_nop 0
	v_cndmask_b32_e32 v107, v186, v107, vcc
	v_cmp_le_i32_e32 vcc, v4, v190
	v_or_b32_e32 v4, 18, v2
	s_nop 0
	v_cndmask_b32_e32 v91, v186, v91, vcc
	v_cmp_le_i32_e32 vcc, v4, v190
	v_or_b32_e32 v4, 50, v2
	s_nop 0
	v_cndmask_b32_e32 v108, v186, v108, vcc
	v_cmp_le_i32_e32 vcc, v4, v190
	v_or_b32_e32 v4, 19, v2
	s_nop 0
	v_cndmask_b32_e32 v92, v186, v92, vcc
	v_cmp_le_i32_e32 vcc, v4, v190
	v_or_b32_e32 v4, 51, v2
	s_nop 0
	v_cndmask_b32_e32 v109, v186, v109, vcc
	v_cmp_le_i32_e32 vcc, v4, v190
	v_or_b32_e32 v4, 24, v2
	s_nop 0
	v_cndmask_b32_e32 v93, v186, v93, vcc
	v_cmp_le_i32_e32 vcc, v4, v190
	v_or_b32_e32 v4, 56, v2
	s_nop 0
	v_cndmask_b32_e32 v110, v186, v110, vcc
	v_cmp_le_i32_e32 vcc, v4, v190
	v_or_b32_e32 v4, 25, v2
	s_nop 0
	v_cndmask_b32_e32 v94, v186, v94, vcc
	v_cmp_le_i32_e32 vcc, v4, v190
	v_or_b32_e32 v4, 57, v2
	s_nop 0
	v_cndmask_b32_e32 v111, v186, v111, vcc
	v_cmp_le_i32_e32 vcc, v4, v190
	v_or_b32_e32 v4, 26, v2
	s_nop 0
	v_cndmask_b32_e32 v95, v186, v95, vcc
	v_cmp_le_i32_e32 vcc, v4, v190
	v_or_b32_e32 v4, 58, v2
	s_nop 0
	v_cndmask_b32_e32 v112, v186, v112, vcc
	v_cmp_le_i32_e32 vcc, v4, v190
	v_or_b32_e32 v4, 27, v2
	v_or_b32_e32 v2, 59, v2
	v_cndmask_b32_e32 v96, v186, v96, vcc
	v_cmp_le_i32_e32 vcc, v4, v190
	s_nop 1
	v_cndmask_b32_e32 v113, v186, v113, vcc
	v_cmp_le_i32_e32 vcc, v2, v190
	s_nop 1
	v_cndmask_b32_e32 v97, v186, v97, vcc

; #define LAS __attribute__((address_space(3)))
; DI float fexp2(float x) { return __builtin_amdgcn_exp2f(x); }
; DI float half_max(float v) { return fmaxf(v, __shfl_xor(v, 32)); }
; DI void flash_pv(FState& st, f32x16& p0, f32x16& p1, bool rowon, const LAS unsigned char* vb, int lane) {
;     float mx = fmaxf(p0[0], p1[0]);
; #pragma unroll
;     for (int r = 1; r < 16; ++r) asm("v_max3_f32 %0, %1, %2, %3" : "=v"(mx) : "v"(mx), "v"(p0[r]), "v"(p1[r]));
;     mx = half_max(mx);
;     mx = rowon ? mx : NINF;
;     const bool upd = mx > st.m + THR_RAW;
;     if (__any(upd)) {
;         const float mn = upd ? mx : st.m;
;         const float alpha = upd ? fexp2((st.m - mn) * SM_C) : 1.0f;
;         st.m = mn; st.l *= alpha;
; #pragma unroll
;         for (int r = 0; r < 16; ++r) { st.o0[r] *= alpha; st.o1[r] *= alpha; }
;     }
.Lnq_772:
	v_max_f32_e32 v2, v98, v82
	s_waitcnt lgkmcnt(3)
	v_mfma_f32_32x32x16_bf16 v[130:145], v[226:229], v[146:149], 0
	v_max3_f32 v2, v2, v99, v83
	v_max3_f32 v2, v2, v100, v84
	v_max3_f32 v2, v2, v101, v85
	v_max3_f32 v2, v2, v102, v86
	s_waitcnt lgkmcnt(2)
	v_mfma_f32_32x32x16_bf16 v[114:129], v[230:233], v[146:149], 0
	ds_read_b128 v[226:229], v223 offset:32768
	ds_read_b128 v[230:233], v223 offset:36864
	v_max3_f32 v2, v2, v103, v87
	v_max3_f32 v2, v2, v104, v88
	v_max3_f32 v2, v2, v105, v89
	v_max3_f32 v2, v2, v106, v90
	s_waitcnt lgkmcnt(3)
	v_mfma_f32_32x32x16_bf16 v[130:145], v[234:237], v[150:153], v[130:145]
	v_max3_f32 v2, v2, v107, v91
	v_max3_f32 v2, v2, v108, v92
	v_max3_f32 v2, v2, v109, v93
	v_max3_f32 v2, v2, v110, v94
	s_waitcnt lgkmcnt(2)
	v_mfma_f32_32x32x16_bf16 v[114:129], v[238:241], v[150:153], v[114:129]
	ds_read_b128 v[234:237], v224 offset:32768
	ds_read_b128 v[238:241], v224 offset:36864
	v_max3_f32 v2, v2, v111, v95
	v_max3_f32 v2, v2, v112, v96
	v_max3_f32 v2, v2, v113, v97
	v_mov_b32_e32 v4, v2
	s_nop 1
	v_permlane32_swap_b32_e32 v4, v2
	s_nop 0
	v_max_f32_e32 v2, v2, v4
	v_cndmask_b32_e64 v2, v186, v2, s[8:9]
	v_add_f32_e32 v4, 0x42317218, v216
	v_cmp_gt_f32_e32 vcc, v2, v4
	s_cbranch_vccz .Lnq_774
	s_nop 0
	v_cndmask_b32_e32 v4, v216, v2, vcc
	v_sub_f32_e32 v2, v216, v4
	v_mul_f32_e32 v2, 0x3e38aa3b, v2
	v_exp_f32_e32 v2, v2
	v_mov_b32_e32 v216, v4
	v_cndmask_b32_e32 v2, 1.0, v2, vcc
	v_mul_f32_e32 v214, v214, v2
	v_pk_mul_f32 v[80:81], v[80:81], v[2:3] op_sel_hi:[1,0]
	v_pk_mul_f32 v[78:79], v[78:79], v[2:3] op_sel_hi:[1,0]
	v_pk_mul_f32 v[76:77], v[76:77], v[2:3] op_sel_hi:[1,0]
	v_pk_mul_f32 v[74:75], v[74:75], v[2:3] op_sel_hi:[1,0]
	v_pk_mul_f32 v[72:73], v[72:73], v[2:3] op_sel_hi:[1,0]
	v_pk_mul_f32 v[70:71], v[70:71], v[2:3] op_sel_hi:[1,0]
	v_pk_mul_f32 v[68:69], v[68:69], v[2:3] op_sel_hi:[1,0]
	v_pk_mul_f32 v[66:67], v[66:67], v[2:3] op_sel_hi:[1,0]
	v_pk_mul_f32 v[64:65], v[64:65], v[2:3] op_sel_hi:[1,0]
	v_pk_mul_f32 v[62:63], v[62:63], v[2:3] op_sel_hi:[1,0]
	v_pk_mul_f32 v[60:61], v[60:61], v[2:3] op_sel_hi:[1,0]
	v_pk_mul_f32 v[58:59], v[58:59], v[2:3] op_sel_hi:[1,0]
	v_pk_mul_f32 v[56:57], v[56:57], v[2:3] op_sel_hi:[1,0]
	v_pk_mul_f32 v[54:55], v[54:55], v[2:3] op_sel_hi:[1,0]
	v_pk_mul_f32 v[52:53], v[52:53], v[2:3] op_sel_hi:[1,0]
	v_pk_mul_f32 v[50:51], v[50:51], v[2:3] op_sel_hi:[1,0]

.Lnq_785:
	s_add_i32 s10, s52, 3
	s_cmp_gt_u32 s76, s69
	s_cselect_b64 s[8:9], -1, 0
	s_and_b64 vcc, s[8:9], exec
	s_cselect_b32 s8, s10, s76
	v_lshl_or_b32 v2, s8, 6, v194
	s_mov_b64 s[10:11], -1
	s_cbranch_vccnz .Lnq_789
	v_bfe_u32 v4, v196, s76, 1
	v_cmp_eq_u32_e64 s[8:9], 1, v4
	s_cmp_lg_u32 s71, s74
	s_cbranch_scc1 .Lnq_788
	v_cmp_le_i32_e32 vcc, v2, v190
	v_or_b32_e32 v4, 32, v2
	s_nop 0
	v_cndmask_b32_e32 v130, v186, v130, vcc
	v_cmp_le_i32_e32 vcc, v4, v190
	v_or_b32_e32 v4, 33, v2
	s_nop 0
	v_cndmask_b32_e32 v114, v186, v114, vcc
	v_cmp_lt_i32_e32 vcc, v2, v190
	s_nop 1
	v_cndmask_b32_e32 v131, v186, v131, vcc
	v_cmp_le_i32_e32 vcc, v4, v190
	v_or_b32_e32 v4, 2, v2
	s_nop 0
	v_cndmask_b32_e32 v115, v186, v115, vcc
	v_cmp_le_i32_e32 vcc, v4, v190
	v_or_b32_e32 v4, 34, v2
	s_nop 0
	v_cndmask_b32_e32 v132, v186, v132, vcc
	v_cmp_le_i32_e32 vcc, v4, v190
	v_or_b32_e32 v4, 3, v2
	s_nop 0
	v_cndmask_b32_e32 v116, v186, v116, vcc
	v_cmp_le_i32_e32 vcc, v4, v190
	v_or_b32_e32 v4, 35, v2
	s_nop 0
	v_cndmask_b32_e32 v133, v186, v133, vcc
	v_cmp_le_i32_e32 vcc, v4, v190
	v_or_b32_e32 v4, 8, v2
	s_nop 0
	v_cndmask_b32_e32 v117, v186, v117, vcc
	v_cmp_le_i32_e32 vcc, v4, v190
	v_or_b32_e32 v4, 40, v2
	s_nop 0
	v_cndmask_b32_e32 v134, v186, v134, vcc
	v_cmp_le_i32_e32 vcc, v4, v190
	v_or_b32_e32 v4, 9, v2
	s_nop 0
	v_cndmask_b32_e32 v118, v186, v118, vcc
	v_cmp_le_i32_e32 vcc, v4, v190
	v_or_b32_e32 v4, 41, v2
	s_nop 0
	v_cndmask_b32_e32 v135, v186, v135, vcc
	v_cmp_le_i32_e32 vcc, v4, v190
	v_or_b32_e32 v4, 10, v2
	s_nop 0
	v_cndmask_b32_e32 v119, v186, v119, vcc
	v_cmp_le_i32_e32 vcc, v4, v190
	v_or_b32_e32 v4, 42, v2
	s_nop 0
	v_cndmask_b32_e32 v136, v186, v136, vcc
	v_cmp_le_i32_e32 vcc, v4, v190
	v_or_b32_e32 v4, 11, v2
	s_nop 0
	v_cndmask_b32_e32 v120, v186, v120, vcc
	v_cmp_le_i32_e32 vcc, v4, v190
	v_or_b32_e32 v4, 43, v2
	s_nop 0
	v_cndmask_b32_e32 v137, v186, v137, vcc
	v_cmp_le_i32_e32 vcc, v4, v190
	v_or_b32_e32 v4, 16, v2
	s_nop 0
	v_cndmask_b32_e32 v121, v186, v121, vcc
	v_cmp_le_i32_e32 vcc, v4, v190
	v_or_b32_e32 v4, 48, v2
	s_nop 0
	v_cndmask_b32_e32 v138, v186, v138, vcc
	v_cmp_le_i32_e32 vcc, v4, v190
	v_or_b32_e32 v4, 17, v2
	s_nop 0
	v_cndmask_b32_e32 v122, v186, v122, vcc
	v_cmp_le_i32_e32 vcc, v4, v190
	v_or_b32_e32 v4, 49, v2
	s_nop 0
	v_cndmask_b32_e32 v139, v186, v139, vcc
	v_cmp_le_i32_e32 vcc, v4, v190
	v_or_b32_e32 v4, 18, v2
	s_nop 0
	v_cndmask_b32_e32 v123, v186, v123, vcc
	v_cmp_le_i32_e32 vcc, v4, v190
	v_or_b32_e32 v4, 50, v2
	s_nop 0
	v_cndmask_b32_e32 v140, v186, v140, vcc
	v_cmp_le_i32_e32 vcc, v4, v190
	v_or_b32_e32 v4, 19, v2
	s_nop 0
	v_cndmask_b32_e32 v124, v186, v124, vcc
	v_cmp_le_i32_e32 vcc, v4, v190
	v_or_b32_e32 v4, 51, v2
	s_nop 0
	v_cndmask_b32_e32 v141, v186, v141, vcc
	v_cmp_le_i32_e32 vcc, v4, v190
	v_or_b32_e32 v4, 24, v2
	s_nop 0
	v_cndmask_b32_e32 v125, v186, v125, vcc
	v_cmp_le_i32_e32 vcc, v4, v190
	v_or_b32_e32 v4, 56, v2
	s_nop 0
	v_cndmask_b32_e32 v142, v186, v142, vcc
	v_cmp_le_i32_e32 vcc, v4, v190
	v_or_b32_e32 v4, 25, v2
	s_nop 0
	v_cndmask_b32_e32 v126, v186, v126, vcc
	v_cmp_le_i32_e32 vcc, v4, v190
	v_or_b32_e32 v4, 57, v2
	s_nop 0
	v_cndmask_b32_e32 v143, v186, v143, vcc
	v_cmp_le_i32_e32 vcc, v4, v190
	v_or_b32_e32 v4, 26, v2
	s_nop 0
	v_cndmask_b32_e32 v127, v186, v127, vcc
	v_cmp_le_i32_e32 vcc, v4, v190
	v_or_b32_e32 v4, 58, v2
	s_nop 0
	v_cndmask_b32_e32 v144, v186, v144, vcc
	v_cmp_le_i32_e32 vcc, v4, v190
	v_or_b32_e32 v4, 27, v2
	s_nop 0
	v_cndmask_b32_e32 v128, v186, v128, vcc
	v_cmp_le_i32_e32 vcc, v4, v190
	v_or_b32_e32 v4, 59, v2
	s_nop 0
	v_cndmask_b32_e32 v145, v186, v145, vcc
	v_cmp_le_i32_e32 vcc, v4, v190
	s_nop 1
	v_cndmask_b32_e32 v129, v186, v129, vcc

; #define LAS __attribute__((address_space(3)))
; #define MFMA32(a, b, c) __builtin_amdgcn_mfma_f32_32x32x16_bf16((a), (b), (c), 0, 0, 0)
; DI float fexp2(float x) { return __builtin_amdgcn_exp2f(x); }
; DI float half_max(float v) { return fmaxf(v, __shfl_xor(v, 32)); }
; DI void flash_qk(const LAS unsigned char* kb, const bf16x8 (&qf)[4], f32x16& p0, f32x16& p1, int r32, int h) {
;     p0 = f16zero(); p1 = f16zero();
;     const int sw = (r32 >> 1) & 7;
; #pragma unroll
;     for (int s = 0; s < 4; ++s) {
;         const int off = r32 * 128 + (((2 * s + h) ^ sw) << 4);
;         const bf16x8 a0 = *(const LAS bf16x8*)(kb + off), a1 = *(const LAS bf16x8*)(kb + off + 4096);
;         p0 = MFMA32(a0, qf[s], p0); p1 = MFMA32(a1, qf[s], p1);
;     }
; }
; DI void flash_pv(FState& st, f32x16& p0, f32x16& p1, bool rowon, const LAS unsigned char* vb, int lane) {
;     float mx = fmaxf(p0[0], p1[0]);
; #pragma unroll
;     for (int r = 1; r < 16; ++r) asm("v_max3_f32 %0, %1, %2, %3" : "=v"(mx) : "v"(mx), "v"(p0[r]), "v"(p1[r]));
;     mx = half_max(mx);
;     mx = rowon ? mx : NINF;
;     const bool upd = mx > st.m + THR_RAW;
;     if (__any(upd)) {
;         const float mn = upd ? mx : st.m;
;         const float alpha = upd ? fexp2((st.m - mn) * SM_C) : 1.0f;
;         st.m = mn; st.l *= alpha;
; #pragma unroll
;         for (int r = 0; r < 16; ++r) { st.o0[r] *= alpha; st.o1[r] *= alpha; }
;     }
.Lnq_793:
	v_max_f32_e32 v2, v130, v114
	s_waitcnt lgkmcnt(3)
	v_mfma_f32_32x32x16_bf16 v[98:113], v[226:229], v[146:149], 0
	v_max3_f32 v2, v2, v131, v115
	v_max3_f32 v2, v2, v132, v116
	v_max3_f32 v2, v2, v133, v117
	v_max3_f32 v2, v2, v134, v118
	s_waitcnt lgkmcnt(2)
	v_mfma_f32_32x32x16_bf16 v[82:97], v[230:233], v[146:149], 0
	ds_read_b128 v[226:229], v223
	ds_read_b128 v[230:233], v223 offset:4096
	v_max3_f32 v2, v2, v135, v119
	v_max3_f32 v2, v2, v136, v120
	v_max3_f32 v2, v2, v137, v121
	v_max3_f32 v2, v2, v138, v122
	s_waitcnt lgkmcnt(3)
	v_mfma_f32_32x32x16_bf16 v[98:113], v[234:237], v[150:153], v[98:113]
	v_max3_f32 v2, v2, v139, v123
	v_max3_f32 v2, v2, v140, v124
	v_max3_f32 v2, v2, v141, v125
	v_max3_f32 v2, v2, v142, v126
	s_waitcnt lgkmcnt(2)
	v_mfma_f32_32x32x16_bf16 v[82:97], v[238:241], v[150:153], v[82:97]
	ds_read_b128 v[234:237], v224
	ds_read_b128 v[238:241], v224 offset:4096
	v_max3_f32 v2, v2, v143, v127
	v_max3_f32 v2, v2, v144, v128
	v_max3_f32 v2, v2, v145, v129
	v_mov_b32_e32 v4, v2
	s_nop 1
	v_permlane32_swap_b32_e32 v4, v2
	s_nop 0
	v_max_f32_e32 v2, v2, v4
	v_cndmask_b32_e64 v2, v186, v2, s[8:9]
	v_add_f32_e32 v4, 0x42317218, v216
	v_cmp_gt_f32_e32 vcc, v2, v4
	s_cbranch_vccz .Lnq_795
	s_nop 0
	v_cndmask_b32_e32 v4, v216, v2, vcc
	v_sub_f32_e32 v2, v216, v4
	v_mul_f32_e32 v2, 0x3e38aa3b, v2
	v_exp_f32_e32 v2, v2
	v_mov_b32_e32 v216, v4
	v_cndmask_b32_e32 v2, 1.0, v2, vcc
	v_mul_f32_e32 v214, v214, v2
	v_pk_mul_f32 v[80:81], v[80:81], v[2:3] op_sel_hi:[1,0]
	v_pk_mul_f32 v[78:79], v[78:79], v[2:3] op_sel_hi:[1,0]
	v_pk_mul_f32 v[76:77], v[76:77], v[2:3] op_sel_hi:[1,0]
	v_pk_mul_f32 v[74:75], v[74:75], v[2:3] op_sel_hi:[1,0]
	v_pk_mul_f32 v[72:73], v[72:73], v[2:3] op_sel_hi:[1,0]
	v_pk_mul_f32 v[70:71], v[70:71], v[2:3] op_sel_hi:[1,0]
	v_pk_mul_f32 v[68:69], v[68:69], v[2:3] op_sel_hi:[1,0]
	v_pk_mul_f32 v[66:67], v[66:67], v[2:3] op_sel_hi:[1,0]
	v_pk_mul_f32 v[64:65], v[64:65], v[2:3] op_sel_hi:[1,0]
	v_pk_mul_f32 v[62:63], v[62:63], v[2:3] op_sel_hi:[1,0]
	v_pk_mul_f32 v[60:61], v[60:61], v[2:3] op_sel_hi:[1,0]
	v_pk_mul_f32 v[58:59], v[58:59], v[2:3] op_sel_hi:[1,0]
	v_pk_mul_f32 v[56:57], v[56:57], v[2:3] op_sel_hi:[1,0]
	v_pk_mul_f32 v[54:55], v[54:55], v[2:3] op_sel_hi:[1,0]
	v_pk_mul_f32 v[52:53], v[52:53], v[2:3] op_sel_hi:[1,0]
	v_pk_mul_f32 v[50:51], v[50:51], v[2:3] op_sel_hi:[1,0]
